# backward-pass epilogue of both recurrence output kernels: gate/gain/output-gate loads batched
# speedup vs baseline: 1.1022x; 1.0010x over previous
; template <int MX, bool OUT>
; DI void rec_chunk(const Params& p, int l, int b, int h, int dir, int T0, unsigned char* smem, f32x4 (&St)[4], float& nst, float& dtot, int tid, const RecRaw& raw) {
;     ...
; #pragma unroll
;     for (int ks = 0; ks < 2; ++ks) {
;       const bf16x8 fb = *(const bf16x8*)(smem + L_QS + swz(t, ks * 4 + g));
; #pragma unroll
;       for (int a = 0; a < 4; ++a) {
;         const bf16x8 fa = *(const bf16x8*)(smem + L_STT + swz(16 * a + col, ks * 4 + g));
;         O[a] = MFMA16(fa, fb, O[a]);
;       }
;     }
;     if (MX == 1) {
;       const float inv = 1.f / fmaxf(fabsf(den), 1.f);
; #pragma unroll
;       for (int a = 0; a < 4; ++a)
; #pragma unroll
;         for (int j = 0; j < 4; ++j) O[a][j] *= inv;
;     }
;     if (dir == 0) {
; #pragma unroll
;       for (int a = 0; a < 4; ++a) *(uint2*)(MIX + kblk((int)orow, cb + 16 * a + 4 * g, ROWS)) = make_uint2(pk2(O[a][0], O[a][1]), pk2(O[a][2], O[a][3]));
;     } else {
;       float ss = 0.f;
; #pragma unroll
;       for (int a = 0; a < 4; ++a) {
;         const uint2 u = *(const uint2*)(MIX + kblk((int)orow, cb + 16 * a + 4 * g, ROWS));
;         O[a][0] += __uint_as_float(u.x << 16); O[a][1] += __uint_as_float(u.x & 0xffff0000u);
;         O[a][2] += __uint_as_float(u.y << 16); O[a][3] += __uint_as_float(u.y & 0xffff0000u);
; #pragma unroll
;         for (int j = 0; j < 4; ++j) ss += O[a][j] * O[a][j];
;       }
;       ss += __shfl_xor(ss, 16);
;       ss += __shfl_xor(ss, 32);
;       const float rstd = rsqrtf(ss * (1.f / 64.f) + EPS);
;       const float* gvec = (MX ? p.ml_g : p.hg_g) + l * 64;
; #pragma unroll
;       for (int a = 0; a < 4; ++a) {
;         const int v0 = 16 * a + 4 * g;
;         const uint2 gt = *(const uint2*)(prow + GATE + cb + v0);
;         const float4 gg = *(const float4*)(gvec + v0);
;         float y0 = O[a][0] * rstd * gg.x * siluf_(__uint_as_float(gt.x << 16));
;         float y1 = O[a][1] * rstd * gg.y * siluf_(__uint_as_float(gt.x & 0xffff0000u));
;         float y2 = O[a][2] * rstd * gg.z * siluf_(__uint_as_float(gt.y << 16));
;         float y3 = O[a][3] * rstd * gg.w * siluf_(__uint_as_float(gt.y & 0xffff0000u));
;         if (MX == 1) {
;           const uint2 og = *(const uint2*)(prow + D_OG + h * 64 + v0);
;           y0 *= sigmoidf_(__uint_as_float(og.x << 16)); y1 *= sigmoidf_(__uint_as_float(og.x & 0xffff0000u));
.LBB0_928:
	s_or_b64 exec, exec, s[0:1]
	ds_read_b128 v[42:45], v242 offset:32768
	ds_read_b128 v[46:49], v240 offset:57344
	ds_read_b128 v[50:53], v240 offset:59392
	s_add_i32 s0, s54, -1
	v_mov_b32_e32 v40, s0
	v_cndmask_b32_e64 v40, v93, v40, s[40:41]
	s_waitcnt lgkmcnt(1)
	v_mfma_f32_16x16x32_bf16 v[46:49], v[46:49], v[42:45], v[56:59]
	v_lshlrev_b32_e32 v40, 6, v40
	v_add_u32_e32 v40, s49, v40
	v_mov_b32_e32 v41, v161
	ds_read_b128 v[54:57], v240 offset:61440
	s_waitcnt lgkmcnt(1)
	v_mfma_f32_16x16x32_bf16 v[50:53], v[50:53], v[42:45], v[60:63]
	v_lshl_add_u64 v[40:41], v[40:41], 0, v[84:85]
	s_nop 1
	ds_read_b128 v[58:61], v240 offset:63488
	s_waitcnt lgkmcnt(1)
	v_mfma_f32_16x16x32_bf16 v[54:57], v[54:57], v[42:45], v[64:67]
	s_waitcnt lgkmcnt(0)
	v_mfma_f32_16x16x32_bf16 v[42:45], v[58:61], v[42:45], v[72:75]
	ds_read_b128 v[58:61], v241 offset:32768
	ds_read_b128 v[62:65], v239 offset:57344
	s_waitcnt lgkmcnt(0)
	v_mfma_f32_16x16x32_bf16 v[46:49], v[62:65], v[58:61], v[46:49]
	ds_read_b128 v[62:65], v239 offset:59392
	s_waitcnt lgkmcnt(0)
	v_mfma_f32_16x16x32_bf16 v[50:53], v[62:65], v[58:61], v[50:53]
	ds_read_b128 v[62:65], v239 offset:61440
	s_waitcnt lgkmcnt(0)
	v_mfma_f32_16x16x32_bf16 v[62:65], v[62:65], v[58:61], v[54:57]
	s_nop 2
	ds_read_b128 v[54:57], v239 offset:63488
	s_waitcnt lgkmcnt(0)
	v_mfma_f32_16x16x32_bf16 v[42:45], v[54:57], v[58:61], v[42:45]
	v_add_f32_e32 v54, v95, v100
	v_max_f32_e64 v54, |v54|, 1.0
	v_div_scale_f32 v55, s[0:1], v54, v54, 1.0
	v_rcp_f32_e32 v56, v55
	s_mov_b64 s[0:1], -1
	v_fma_f32 v57, -v55, v56, 1.0
	v_fmac_f32_e32 v56, v57, v56
	v_div_scale_f32 v57, vcc, 1.0, v54, 1.0
	v_mul_f32_e32 v58, v57, v56
	v_fma_f32 v59, -v55, v58, v57
	v_fmac_f32_e32 v58, v59, v56
	v_fma_f32 v55, -v55, v58, v57
	v_div_fmas_f32 v55, v55, v56, v58
	v_div_fixup_f32 v60, v55, v54, 1.0
	v_pk_mul_f32 v[54:55], v[60:61], v[46:47] op_sel_hi:[0,1]
	v_pk_mul_f32 v[46:47], v[60:61], v[42:43] op_sel_hi:[0,1]
	v_ashrrev_i32_e32 v43, 31, v40
	v_mov_b32_e32 v42, v40
	v_pk_mul_f32 v[58:59], v[60:61], v[48:49] op_sel_hi:[0,1]
	v_pk_mul_f32 v[50:51], v[60:61], v[50:51] op_sel_hi:[0,1]
	v_pk_mul_f32 v[56:57], v[60:61], v[52:53] op_sel_hi:[0,1]
	v_pk_mul_f32 v[48:49], v[60:61], v[62:63] op_sel_hi:[0,1]
	v_pk_mul_f32 v[52:53], v[60:61], v[64:65] op_sel_hi:[0,1]
	v_pk_mul_f32 v[44:45], v[60:61], v[44:45] op_sel_hi:[0,1]
	v_lshl_add_u64 v[60:61], v[42:43], 0, s[42:43]
	v_lshl_add_u64 v[62:63], v[42:43], 0, s[28:29]
	v_lshl_add_u64 v[42:43], v[42:43], 0, s[30:31]
	s_andn2_b64 vcc, exec, s[12:13]
	v_lshlrev_b64 v[64:65], 6, v[60:61]
	v_lshlrev_b64 v[62:63], 6, v[62:63]
	v_lshlrev_b64 v[60:61], 6, v[42:43]
	s_cbranch_vccnz .LBB0_930
	v_lshl_add_u64 v[102:103], v[90:91], 0, v[62:63]
	global_load_dwordx2 v[66:67], v[102:103], off
	v_mov_b64_e32 v[42:43], s[24:25]
	v_mad_u64_u32 v[42:43], s[0:1], v40, s33, v[42:43]
	v_mad_i32_i24 v43, v41, s33, v43
	s_mov_b64 s[0:1], 0x1a20
	v_mov_b32_e32 v93, v161
	v_lshl_add_u64 v[74:75], v[42:43], 0, s[0:1]
	v_lshl_add_u64 v[104:105], v[74:75], 0, s[2:3]
	v_lshl_add_u64 v[74:75], v[74:75], 0, v[92:93]
	v_lshl_add_u64 v[106:107], v[86:87], 0, v[64:65]
	v_lshl_add_u64 v[74:75], v[74:75], 0, s[2:3]
	global_load_dwordx2 v[40:41], v[106:107], off
	s_mov_b32 s21, s3
	v_lshl_add_u64 v[42:43], v[42:43], 0, s[20:21]
	v_lshl_add_u64 v[42:43], v[42:43], 0, v[92:93]
	s_mov_b64 s[0:1], 0x1820
	v_lshl_add_u64 v[104:105], v[104:105], 0, v[92:93]
	global_load_dwordx2 v[74:75], v[74:75], off
	s_waitcnt vmcnt(0) lgkmcnt(0)
	v_lshlrev_b32_e32 v100, 16, v66
	v_and_b32_e32 v101, 0xffff0000, v66
	v_lshlrev_b32_e32 v108, 16, v67
	v_and_b32_e32 v109, 0xffff0000, v67
	v_lshl_add_u64 v[66:67], s[22:23], 0, v[60:61]
	v_lshl_add_u64 v[72:73], v[66:67], 0, v[92:93]
	global_load_dwordx2 v[68:69], v[72:73], off
	v_lshlrev_b32_e32 v128, 16, v40
	v_and_b32_e32 v129, 0xffff0000, v40
	v_lshlrev_b32_e32 v40, 16, v41
	v_and_b32_e32 v41, 0xffff0000, v41
	v_pk_add_f32 v[128:129], v[54:55], v[128:129]
	v_lshlrev_b32_e32 v95, 16, v74
	v_and_b32_e32 v243, 0xffff0000, v74
	v_lshlrev_b32_e32 v130, 16, v75
	v_and_b32_e32 v131, 0xffff0000, v75
	v_lshl_add_u64 v[74:75], v[42:43], 0, s[0:1]
	global_load_dwordx2 v[200:201], v[104:105], off offset:32
	global_load_dwordx2 v[202:203], v[104:105], off offset:64
	global_load_dwordx2 v[204:205], v[104:105], off offset:96
	global_load_dwordx2 v[206:207], v[74:75], off offset:32
	global_load_dwordx2 v[208:209], v[74:75], off offset:64
	global_load_dword v199, v[74:75], off offset:96
	global_load_dword v210, v[74:75], off offset:100
	v_add_co_u32_e32 v42, vcc, s16, v42
	v_mul_f32_e32 v120, 0xbfb8aa3b, v130
	s_nop 0
	v_addc_co_u32_e32 v43, vcc, 0, v43, vcc
	v_mul_f32_e32 v121, 0xbfb8aa3b, v131
	global_load_dwordx2 v[42:43], v[42:43], off offset:2080
	v_exp_f32_e32 v120, v120
	v_exp_f32_e32 v121, v121
	s_waitcnt vmcnt(0) lgkmcnt(0)
; DI size_t kblk(int row, int col, int nrows) { return ((size_t)(col >> 5) * nrows + row) * 32 + (col & 31); }
; DI float sigmoidf_(float z) { return 1.f / (1.f + __expf(-z)); }
; DI float siluf_(float z) { return z / (1.f + __expf(-z)); }
; template <int MX, bool OUT>
; DI void rec_chunk(const Params& p, int l, int b, int h, int dir, int T0, unsigned char* smem, f32x4 (&St)[4], float& nst, float& dtot, int tid, const RecRaw& raw) {
;     ...
;       float ss = 0.f;
; #pragma unroll
;       for (int a = 0; a < 4; ++a) {
;         const uint2 u = *(const uint2*)(MIX + kblk((int)orow, cb + 16 * a + 4 * g, ROWS));
;         O[a][0] += __uint_as_float(u.x << 16); O[a][1] += __uint_as_float(u.x & 0xffff0000u);
;         O[a][2] += __uint_as_float(u.y << 16); O[a][3] += __uint_as_float(u.y & 0xffff0000u);
; #pragma unroll
;         for (int j = 0; j < 4; ++j) ss += O[a][j] * O[a][j];
;       }
;       ss += __shfl_xor(ss, 16);
;       ss += __shfl_xor(ss, 32);
;       const float rstd = rsqrtf(ss * (1.f / 64.f) + EPS);
;       const float* gvec = (MX ? p.ml_g : p.hg_g) + l * 64;
; #pragma unroll
;       for (int a = 0; a < 4; ++a) {
;         const int v0 = 16 * a + 4 * g;
;         const uint2 gt = *(const uint2*)(prow + GATE + cb + v0);
;         const float4 gg = *(const float4*)(gvec + v0);
;         float y0 = O[a][0] * rstd * gg.x * siluf_(__uint_as_float(gt.x << 16));
;         float y1 = O[a][1] * rstd * gg.y * siluf_(__uint_as_float(gt.x & 0xffff0000u));
;         float y2 = O[a][2] * rstd * gg.z * siluf_(__uint_as_float(gt.y << 16));
;         float y3 = O[a][3] * rstd * gg.w * siluf_(__uint_as_float(gt.y & 0xffff0000u));
;         if (MX == 1) {
;           const uint2 og = *(const uint2*)(prow + D_OG + h * 64 + v0);
;           y0 *= sigmoidf_(__uint_as_float(og.x << 16)); y1 *= sigmoidf_(__uint_as_float(og.x & 0xffff0000u));
;           y2 *= sigmoidf_(__uint_as_float(og.y << 16)); y3 *= sigmoidf_(__uint_as_float(og.y & 0xffff0000u));
	v_lshlrev_b32_e32 v110, 16, v68
	v_and_b32_e32 v111, 0xffff0000, v68
	v_pk_add_f32 v[120:121], v[120:121], 1.0 op_sel_hi:[1,0]
	v_lshlrev_b32_e32 v112, 16, v69
	v_div_scale_f32 v132, s[0:1], v121, v121, v131
	v_rcp_f32_e32 v133, v132
	v_and_b32_e32 v113, 0xffff0000, v69
	global_load_dwordx2 v[68:69], v[72:73], off offset:32
	v_pk_add_f32 v[110:111], v[48:49], v[110:111]
	v_fma_f32 v244, -v132, v133, 1.0
	v_fmac_f32_e32 v133, v244, v133
	v_div_scale_f32 v244, vcc, v131, v121, v131
	v_mul_f32_e32 v245, v244, v133
	v_fma_f32 v246, -v132, v245, v244
	v_fmac_f32_e32 v245, v246, v133
	v_fma_f32 v132, -v132, v245, v244
	v_div_fmas_f32 v132, v132, v133, v245
	v_div_fixup_f32 v121, v132, v121, v131
	v_div_scale_f32 v131, s[0:1], v120, v120, v130
	v_rcp_f32_e32 v132, v131
	v_pk_mul_f32 v[250:251], v[110:111], v[110:111]
	v_lshlrev_b32_e32 v118, 16, v42
	v_and_b32_e32 v42, 0xffff0000, v42
	v_fma_f32 v133, -v131, v132, 1.0
	v_fmac_f32_e32 v132, v133, v132
	v_div_scale_f32 v133, vcc, v130, v120, v130
	v_mul_f32_e32 v244, v133, v132
	v_fma_f32 v245, -v131, v244, v133
	v_fmac_f32_e32 v244, v245, v132
	v_fma_f32 v131, -v131, v244, v133
	v_div_fmas_f32 v131, v131, v132, v244
	v_mul_f32_e32 v132, 0xbfb8aa3b, v95
	v_mul_f32_e32 v133, 0xbfb8aa3b, v243
	v_exp_f32_e32 v132, v132
	v_exp_f32_e32 v133, v133
	v_div_fixup_f32 v120, v131, v120, v130
	v_pk_mul_f32 v[130:131], v[128:129], v[128:129]
	v_mul_f32_e32 v118, 0xbfb8aa3b, v118
	v_pk_add_f32 v[132:133], v[132:133], 1.0 op_sel_hi:[1,0]
	v_mul_f32_e32 v42, 0xbfb8aa3b, v42
	v_div_scale_f32 v244, s[0:1], v133, v133, v243
	v_rcp_f32_e32 v245, v244
	v_add_f32_e32 v93, v130, v131
	v_exp_f32_e32 v126, v118
	v_exp_f32_e32 v127, v42
	v_fma_f32 v246, -v244, v245, 1.0
	v_fmac_f32_e32 v245, v246, v245
	v_div_scale_f32 v246, vcc, v243, v133, v243
	v_mul_f32_e32 v247, v246, v245
	v_fma_f32 v248, -v244, v247, v246
	v_fmac_f32_e32 v247, v248, v245
	v_fma_f32 v244, -v244, v247, v246
	v_div_fmas_f32 v244, v244, v245, v247
	v_div_fixup_f32 v133, v244, v133, v243
	v_div_scale_f32 v243, s[0:1], v132, v132, v95
	v_rcp_f32_e32 v244, v243
	v_lshlrev_b32_e32 v42, 16, v43
	v_pk_add_f32 v[118:119], v[58:59], v[40:41]
	v_pk_add_f32 v[248:249], v[50:51], v[100:101]
	v_fma_f32 v245, -v243, v244, 1.0
	v_fmac_f32_e32 v244, v245, v244
	v_div_scale_f32 v245, vcc, v95, v132, v95
	v_mul_f32_e32 v246, v245, v244
	v_fma_f32 v247, -v243, v246, v245
	v_fmac_f32_e32 v246, v247, v244
	v_fma_f32 v243, -v243, v246, v245
	v_div_fmas_f32 v243, v243, v244, v246
	v_div_fixup_f32 v132, v243, v132, v95
	v_pk_mul_f32 v[100:101], v[248:249], v[248:249]
	v_mul_f32_e32 v42, 0xbfb8aa3b, v42
	v_pk_mul_f32 v[122:123], v[118:119], v[118:119]
	v_exp_f32_e32 v124, v42
	v_and_b32_e32 v42, 0xffff0000, v43
	v_add_f32_e32 v93, v93, v122
	v_mul_f32_e32 v42, 0xbfb8aa3b, v42
	v_add_f32_e32 v93, v123, v93
	v_pk_add_f32 v[126:127], v[126:127], 1.0 op_sel_hi:[1,0]
	v_exp_f32_e32 v125, v42
	v_div_scale_f32 v95, s[0:1], v127, v127, 1.0
	global_load_dwordx4 v[40:43], v[88:89], off
	v_rcp_f32_e32 v243, v95
	v_pk_add_f32 v[124:125], v[124:125], 1.0 op_sel_hi:[1,0]
	v_add_f32_e32 v93, v100, v93
	v_add_f32_e32 v93, v101, v93
	v_fma_f32 v244, -v95, v243, 1.0
	v_fmac_f32_e32 v243, v244, v243
	v_div_scale_f32 v244, vcc, 1.0, v127, 1.0
	v_mul_f32_e32 v245, v244, v243
	v_fma_f32 v246, -v95, v245, v244
	v_fmac_f32_e32 v245, v246, v243
	v_fma_f32 v95, -v95, v245, v244
	v_div_fmas_f32 v95, v95, v243, v245
	v_div_fixup_f32 v127, v95, v127, 1.0
	v_div_scale_f32 v95, s[0:1], v126, v126, 1.0
	v_rcp_f32_e32 v243, v95
	s_waitcnt vmcnt(0) lgkmcnt(0)
	v_lshlrev_b32_e32 v70, 16, v68
	v_and_b32_e32 v71, 0xffff0000, v68
	v_pk_add_f32 v[70:71], v[46:47], v[70:71]
	v_fma_f32 v244, -v95, v243, 1.0
	v_fmac_f32_e32 v243, v244, v243
	v_div_scale_f32 v244, vcc, 1.0, v126, 1.0
	v_mul_f32_e32 v245, v244, v243
	v_fma_f32 v246, -v95, v245, v244
	v_fmac_f32_e32 v245, v246, v243
	v_fma_f32 v95, -v95, v245, v244
	v_div_fmas_f32 v95, v95, v243, v245
	v_div_fixup_f32 v126, v95, v126, 1.0
	v_div_scale_f32 v95, s[0:1], v125, v125, 1.0
	v_rcp_f32_e32 v243, v95
	v_lshlrev_b32_e32 v68, 16, v69
	v_and_b32_e32 v69, 0xffff0000, v69
	v_pk_mul_f32 v[114:115], v[70:71], v[70:71]
	v_fma_f32 v244, -v95, v243, 1.0
	v_fmac_f32_e32 v243, v244, v243
	v_div_scale_f32 v244, vcc, 1.0, v125, 1.0
	v_mul_f32_e32 v245, v244, v243
	v_fma_f32 v246, -v95, v245, v244
	v_fmac_f32_e32 v245, v246, v243
	v_fma_f32 v95, -v95, v245, v244
	v_div_fmas_f32 v95, v95, v243, v245
	v_div_fixup_f32 v125, v95, v125, 1.0
	v_div_scale_f32 v95, s[0:1], v124, v124, 1.0
	v_rcp_f32_e32 v243, v95
	v_pk_add_f32 v[68:69], v[44:45], v[68:69]
	v_fma_f32 v244, -v95, v243, 1.0
	v_fmac_f32_e32 v243, v244, v243
	v_div_scale_f32 v244, vcc, 1.0, v124, 1.0
	v_mul_f32_e32 v245, v244, v243
	v_fma_f32 v246, -v95, v245, v244
	v_fmac_f32_e32 v245, v246, v243
	v_fma_f32 v95, -v95, v245, v244
	v_div_fmas_f32 v95, v95, v243, v245
	v_pk_add_f32 v[244:245], v[56:57], v[108:109]
	v_pk_add_f32 v[108:109], v[52:53], v[112:113]
	v_pk_mul_f32 v[246:247], v[244:245], v[244:245]
	v_pk_mul_f32 v[112:113], v[108:109], v[108:109]
	v_add_f32_e32 v93, v246, v93
	v_add_f32_e32 v93, v247, v93
	v_add_f32_e32 v93, v250, v93
	v_add_f32_e32 v93, v251, v93
	v_add_f32_e32 v93, v112, v93
	v_add_f32_e32 v93, v113, v93
	v_add_f32_e32 v93, v114, v93
	v_pk_mul_f32 v[116:117], v[68:69], v[68:69]
	v_add_f32_e32 v93, v115, v93
	v_add_f32_e32 v93, v116, v93
	v_add_f32_e32 v93, v117, v93
	v_div_fixup_f32 v124, v95, v124, 1.0
	ds_bpermute_b32 v95, v149, v93
	s_waitcnt lgkmcnt(0)
	v_add_f32_e32 v93, v93, v95
	ds_bpermute_b32 v95, v150, v93
	s_waitcnt lgkmcnt(0)
; DI size_t kblk(int row, int col, int nrows) { return ((size_t)(col >> 5) * nrows + row) * 32 + (col & 31); }
; DI unsigned pk2(float a, float b) { hwf32x2 f = {a, b}; hwbf16x2 r = __builtin_convertvector(f, hwbf16x2); return __builtin_bit_cast(unsigned, r); }
; DI float sigmoidf_(float z) { return 1.f / (1.f + __expf(-z)); }
; DI float siluf_(float z) { return z / (1.f + __expf(-z)); }
; template <int MX, bool OUT>
; DI void rec_chunk(const Params& p, int l, int b, int h, int dir, int T0, unsigned char* smem, f32x4 (&St)[4], float& nst, float& dtot, int tid, const RecRaw& raw) {
;     ...
;       ss += __shfl_xor(ss, 16);
;       ss += __shfl_xor(ss, 32);
;       const float rstd = rsqrtf(ss * (1.f / 64.f) + EPS);
;       const float* gvec = (MX ? p.ml_g : p.hg_g) + l * 64;
; #pragma unroll
;       for (int a = 0; a < 4; ++a) {
;         const int v0 = 16 * a + 4 * g;
;         const uint2 gt = *(const uint2*)(prow + GATE + cb + v0);
;         const float4 gg = *(const float4*)(gvec + v0);
;         float y0 = O[a][0] * rstd * gg.x * siluf_(__uint_as_float(gt.x << 16));
;         float y1 = O[a][1] * rstd * gg.y * siluf_(__uint_as_float(gt.x & 0xffff0000u));
;         float y2 = O[a][2] * rstd * gg.z * siluf_(__uint_as_float(gt.y << 16));
;         float y3 = O[a][3] * rstd * gg.w * siluf_(__uint_as_float(gt.y & 0xffff0000u));
;         if (MX == 1) {
;           const uint2 og = *(const uint2*)(prow + D_OG + h * 64 + v0);
;           y0 *= sigmoidf_(__uint_as_float(og.x << 16)); y1 *= sigmoidf_(__uint_as_float(og.x & 0xffff0000u));
;           y2 *= sigmoidf_(__uint_as_float(og.y << 16)); y3 *= sigmoidf_(__uint_as_float(og.y & 0xffff0000u));
;         }
;         *(uint2*)(MIX + kblk((int)orow, cb + v0, ROWS)) = make_uint2(pk2(y0, y1), pk2(y2, y3));
	v_add_f32_e32 v93, v93, v95
	v_fmamk_f32 v93, v93, 0x3c800000, v162
	v_cmp_gt_f32_e32 vcc, s38, v93
	v_mul_f32_e32 v95, 0x4b800000, v93
	s_nop 0
	v_cndmask_b32_e32 v93, v93, v95, vcc
	v_rsq_f32_e32 v93, v93
	s_nop 0
	v_mul_f32_e32 v95, 0x45800000, v93
	v_cndmask_b32_e32 v100, v93, v95, vcc
	v_pk_mul_f32 v[112:113], v[128:129], v[100:101] op_sel_hi:[1,0]
	s_nop 0
	v_pk_mul_f32 v[40:41], v[40:41], v[112:113]
	v_pk_mul_f32 v[112:113], v[118:119], v[100:101] op_sel_hi:[1,0]
	v_pk_mul_f32 v[40:41], v[132:133], v[40:41]
	v_pk_mul_f32 v[42:43], v[42:43], v[112:113]
	v_pk_mul_f32 v[40:41], v[126:127], v[40:41]
	v_pk_mul_f32 v[42:43], v[120:121], v[42:43]
	v_cvt_pk_bf16_f32 v40, v40, v41
	v_pk_mul_f32 v[42:43], v[124:125], v[42:43]
	s_nop 0
	v_cvt_pk_bf16_f32 v41, v42, v43
	global_store_dwordx2 v[106:107], v[40:41], off
	s_nop 0
	s_nop 0
	global_load_dwordx4 v[112:115], v[88:89], off offset:64
	v_pk_mul_f32 v[106:107], v[248:249], v[100:101] op_sel_hi:[1,0]
	s_waitcnt vmcnt(0) lgkmcnt(0)
	v_mov_b32_e32 v40, v200
	v_mov_b32_e32 v41, v201
	v_lshlrev_b32_e32 v93, 16, v40
	v_and_b32_e32 v40, 0xffff0000, v40
	v_mul_f32_e32 v42, 0xbfb8aa3b, v93
	v_mul_f32_e32 v43, 0xbfb8aa3b, v40
	v_exp_f32_e32 v42, v42
	v_exp_f32_e32 v43, v43
	v_pk_mul_f32 v[106:107], v[112:113], v[106:107]
	v_pk_add_f32 v[42:43], v[42:43], 1.0 op_sel_hi:[1,0]
	s_nop 0
	v_div_scale_f32 v95, s[0:1], v43, v43, v40
	v_rcp_f32_e32 v101, v95
	s_nop 0
	v_fma_f32 v112, -v95, v101, 1.0
	v_fmac_f32_e32 v101, v112, v101
	v_div_scale_f32 v112, vcc, v40, v43, v40
	v_mul_f32_e32 v113, v112, v101
	v_fma_f32 v116, -v95, v113, v112
	v_fmac_f32_e32 v113, v116, v101
	v_fma_f32 v95, -v95, v113, v112
	v_div_fmas_f32 v95, v95, v101, v113
	v_div_fixup_f32 v43, v95, v43, v40
	v_div_scale_f32 v40, s[0:1], v42, v42, v93
	v_rcp_f32_e32 v95, v40
	s_nop 0
	v_fma_f32 v101, -v40, v95, 1.0
	v_fmac_f32_e32 v95, v101, v95
	v_div_scale_f32 v101, vcc, v93, v42, v93
	v_mul_f32_e32 v112, v101, v95
	v_fma_f32 v113, -v40, v112, v101
	v_fmac_f32_e32 v112, v113, v95
	v_fma_f32 v40, -v40, v112, v101
	v_div_fmas_f32 v40, v40, v95, v112
	v_div_fixup_f32 v42, v40, v42, v93
	v_lshlrev_b32_e32 v93, 16, v41
	v_and_b32_e32 v95, 0xffff0000, v41
	v_mul_f32_e32 v40, 0xbfb8aa3b, v93
	v_mul_f32_e32 v41, 0xbfb8aa3b, v95
	v_exp_f32_e32 v40, v40
	v_exp_f32_e32 v41, v41
	v_pk_mul_f32 v[42:43], v[42:43], v[106:107]
	v_pk_mul_f32 v[106:107], v[244:245], v[100:101] op_sel_hi:[1,0]
	v_pk_add_f32 v[40:41], v[40:41], 1.0 op_sel_hi:[1,0]
	s_nop 0
	v_div_scale_f32 v101, s[0:1], v41, v41, v95
	v_rcp_f32_e32 v112, v101
	v_pk_mul_f32 v[106:107], v[114:115], v[106:107]
	v_fma_f32 v113, -v101, v112, 1.0
	v_fmac_f32_e32 v112, v113, v112
	v_div_scale_f32 v113, vcc, v95, v41, v95
	v_mul_f32_e32 v114, v113, v112
	v_fma_f32 v115, -v101, v114, v113
	v_fmac_f32_e32 v114, v115, v112
	v_fma_f32 v101, -v101, v114, v113
	v_div_fmas_f32 v101, v101, v112, v114
	v_div_fixup_f32 v41, v101, v41, v95
	v_div_scale_f32 v95, s[0:1], v40, v40, v93
	v_rcp_f32_e32 v101, v95
	s_nop 0
	v_fma_f32 v112, -v95, v101, 1.0
	v_fmac_f32_e32 v101, v112, v101
	v_div_scale_f32 v112, vcc, v93, v40, v93
	v_mul_f32_e32 v113, v112, v101
	v_fma_f32 v114, -v95, v113, v112
	v_fmac_f32_e32 v113, v114, v101
	v_fma_f32 v95, -v95, v113, v112
	v_div_fmas_f32 v95, v95, v101, v113
	v_div_fixup_f32 v40, v95, v40, v93
	v_pk_mul_f32 v[40:41], v[40:41], v[106:107]
	s_nop 0
	s_waitcnt lgkmcnt(0)
	v_mov_b32_e32 v106, v206
	v_mov_b32_e32 v107, v207
	v_lshlrev_b32_e32 v93, 16, v106
	v_mul_f32_e32 v93, 0xbfb8aa3b, v93
	v_exp_f32_e32 v112, v93
	v_and_b32_e32 v93, 0xffff0000, v106
	v_mul_f32_e32 v93, 0xbfb8aa3b, v93
	v_exp_f32_e32 v113, v93
	s_nop 0
	v_pk_add_f32 v[112:113], v[112:113], 1.0 op_sel_hi:[1,0]
	s_nop 0
	v_div_scale_f32 v93, s[0:1], v113, v113, 1.0
	v_rcp_f32_e32 v95, v93
	s_nop 0
	v_fma_f32 v101, -v93, v95, 1.0
	v_fmac_f32_e32 v95, v101, v95
	v_div_scale_f32 v101, vcc, 1.0, v113, 1.0
	v_mul_f32_e32 v106, v101, v95
	v_fma_f32 v114, -v93, v106, v101
	v_fmac_f32_e32 v106, v114, v95
	v_fma_f32 v93, -v93, v106, v101
	v_div_fmas_f32 v93, v93, v95, v106
	v_div_fixup_f32 v113, v93, v113, 1.0
	v_div_scale_f32 v93, s[0:1], v112, v112, 1.0
	v_rcp_f32_e32 v95, v93
	s_nop 0
	v_fma_f32 v101, -v93, v95, 1.0
	v_fmac_f32_e32 v95, v101, v95
	v_div_scale_f32 v101, vcc, 1.0, v112, 1.0
	v_mul_f32_e32 v106, v101, v95
	v_fma_f32 v114, -v93, v106, v101
	v_fmac_f32_e32 v106, v114, v95
	v_fma_f32 v93, -v93, v106, v101
	v_div_fmas_f32 v93, v93, v95, v106
	v_div_fixup_f32 v112, v93, v112, 1.0
	v_lshlrev_b32_e32 v93, 16, v107
	v_mul_f32_e32 v93, 0xbfb8aa3b, v93
	v_exp_f32_e32 v106, v93
	v_and_b32_e32 v93, 0xffff0000, v107
	v_mul_f32_e32 v93, 0xbfb8aa3b, v93
	v_exp_f32_e32 v107, v93
	v_pk_mul_f32 v[42:43], v[42:43], v[112:113]
	v_pk_add_f32 v[106:107], v[106:107], 1.0 op_sel_hi:[1,0]
	s_nop 0
	v_div_scale_f32 v93, s[0:1], v107, v107, 1.0
	v_rcp_f32_e32 v95, v93
	v_cvt_pk_bf16_f32 v42, v42, v43
	v_fma_f32 v101, -v93, v95, 1.0
	v_fmac_f32_e32 v95, v101, v95
	v_div_scale_f32 v101, vcc, 1.0, v107, 1.0
	v_mul_f32_e32 v112, v101, v95
	v_fma_f32 v113, -v93, v112, v101
	v_fmac_f32_e32 v112, v113, v95
	v_fma_f32 v93, -v93, v112, v101
	v_div_fmas_f32 v93, v93, v95, v112
	v_div_fixup_f32 v107, v93, v107, 1.0
	v_div_scale_f32 v93, s[0:1], v106, v106, 1.0
	v_rcp_f32_e32 v95, v93
	s_nop 0
	v_fma_f32 v101, -v93, v95, 1.0
	v_fmac_f32_e32 v95, v101, v95
	v_div_scale_f32 v101, vcc, 1.0, v106, 1.0
	v_mul_f32_e32 v112, v101, v95
	v_fma_f32 v113, -v93, v112, v101
	v_fmac_f32_e32 v112, v113, v95
	v_fma_f32 v93, -v93, v112, v101
	v_div_fmas_f32 v93, v93, v95, v112
	v_div_fixup_f32 v106, v93, v106, 1.0
	v_pk_mul_f32 v[40:41], v[40:41], v[106:107]
	s_nop 0
	v_cvt_pk_bf16_f32 v43, v40, v41
	global_store_dwordx2 v[102:103], v[42:43], off
	s_nop 0
	global_load_dwordx4 v[112:115], v[88:89], off offset:128
	v_pk_mul_f32 v[102:103], v[110:111], v[100:101] op_sel_hi:[1,0]
	s_waitcnt vmcnt(0) lgkmcnt(0)
; DI size_t kblk(int row, int col, int nrows) { return ((size_t)(col >> 5) * nrows + row) * 32 + (col & 31); }
; DI unsigned pk2(float a, float b) { hwf32x2 f = {a, b}; hwbf16x2 r = __builtin_convertvector(f, hwbf16x2); return __builtin_bit_cast(unsigned, r); }
; DI float sigmoidf_(float z) { return 1.f / (1.f + __expf(-z)); }
; DI float siluf_(float z) { return z / (1.f + __expf(-z)); }
; template <int MX, bool OUT>
; DI void rec_chunk(const Params& p, int l, int b, int h, int dir, int T0, unsigned char* smem, f32x4 (&St)[4], float& nst, float& dtot, int tid, const RecRaw& raw) {
;     ...
;       for (int a = 0; a < 4; ++a) {
;         const int v0 = 16 * a + 4 * g;
;         const uint2 gt = *(const uint2*)(prow + GATE + cb + v0);
;         const float4 gg = *(const float4*)(gvec + v0);
;         float y0 = O[a][0] * rstd * gg.x * siluf_(__uint_as_float(gt.x << 16));
;         float y1 = O[a][1] * rstd * gg.y * siluf_(__uint_as_float(gt.x & 0xffff0000u));
;         float y2 = O[a][2] * rstd * gg.z * siluf_(__uint_as_float(gt.y << 16));
;         float y3 = O[a][3] * rstd * gg.w * siluf_(__uint_as_float(gt.y & 0xffff0000u));
;         if (MX == 1) {
;           const uint2 og = *(const uint2*)(prow + D_OG + h * 64 + v0);
;           y0 *= sigmoidf_(__uint_as_float(og.x << 16)); y1 *= sigmoidf_(__uint_as_float(og.x & 0xffff0000u));
;           y2 *= sigmoidf_(__uint_as_float(og.y << 16)); y3 *= sigmoidf_(__uint_as_float(og.y & 0xffff0000u));
;         }
;         *(uint2*)(MIX + kblk((int)orow, cb + v0, ROWS)) = make_uint2(pk2(y0, y1), pk2(y2, y3));
	v_mov_b32_e32 v40, v202
	v_mov_b32_e32 v41, v203
	v_lshlrev_b32_e32 v93, 16, v40
	v_and_b32_e32 v40, 0xffff0000, v40
	v_mul_f32_e32 v42, 0xbfb8aa3b, v93
	v_mul_f32_e32 v43, 0xbfb8aa3b, v40
	v_exp_f32_e32 v42, v42
	v_exp_f32_e32 v43, v43
	v_pk_mul_f32 v[102:103], v[102:103], v[112:113]
	v_pk_add_f32 v[42:43], v[42:43], 1.0 op_sel_hi:[1,0]
	s_nop 0
	v_div_scale_f32 v95, s[0:1], v43, v43, v40
	v_rcp_f32_e32 v101, v95
	s_nop 0
	v_fma_f32 v106, -v95, v101, 1.0
	v_fmac_f32_e32 v101, v106, v101
	v_div_scale_f32 v106, vcc, v40, v43, v40
	v_mul_f32_e32 v107, v106, v101
	v_fma_f32 v110, -v95, v107, v106
	v_fmac_f32_e32 v107, v110, v101
	v_fma_f32 v95, -v95, v107, v106
	v_div_fmas_f32 v95, v95, v101, v107
	v_div_fixup_f32 v43, v95, v43, v40
	v_div_scale_f32 v40, s[0:1], v42, v42, v93
	v_rcp_f32_e32 v95, v40
	s_nop 0
	v_fma_f32 v101, -v40, v95, 1.0
	v_fmac_f32_e32 v95, v101, v95
	v_div_scale_f32 v101, vcc, v93, v42, v93
	v_mul_f32_e32 v106, v101, v95
	v_fma_f32 v107, -v40, v106, v101
	v_fmac_f32_e32 v106, v107, v95
	v_fma_f32 v40, -v40, v106, v101
	v_div_fmas_f32 v40, v40, v95, v106
	v_div_fixup_f32 v42, v40, v42, v93
	v_lshlrev_b32_e32 v93, 16, v41
	v_and_b32_e32 v95, 0xffff0000, v41
	v_mul_f32_e32 v40, 0xbfb8aa3b, v93
	v_mul_f32_e32 v41, 0xbfb8aa3b, v95
	v_exp_f32_e32 v40, v40
	v_exp_f32_e32 v41, v41
	v_pk_mul_f32 v[42:43], v[102:103], v[42:43]
	v_pk_mul_f32 v[102:103], v[108:109], v[100:101] op_sel_hi:[1,0]
	v_pk_add_f32 v[40:41], v[40:41], 1.0 op_sel_hi:[1,0]
	s_nop 0
	v_div_scale_f32 v101, s[0:1], v41, v41, v95
	v_rcp_f32_e32 v106, v101
	v_pk_mul_f32 v[102:103], v[102:103], v[114:115]
	v_fma_f32 v107, -v101, v106, 1.0
	v_fmac_f32_e32 v106, v107, v106
	v_div_scale_f32 v107, vcc, v95, v41, v95
	v_mul_f32_e32 v108, v107, v106
	v_fma_f32 v109, -v101, v108, v107
	v_fmac_f32_e32 v108, v109, v106
	v_fma_f32 v101, -v101, v108, v107
	v_div_fmas_f32 v101, v101, v106, v108
	v_div_fixup_f32 v41, v101, v41, v95
	v_div_scale_f32 v95, s[0:1], v40, v40, v93
	v_rcp_f32_e32 v101, v95
	s_nop 0
	v_fma_f32 v106, -v95, v101, 1.0
	v_fmac_f32_e32 v101, v106, v101
	v_div_scale_f32 v106, vcc, v93, v40, v93
	v_mul_f32_e32 v107, v106, v101
	v_fma_f32 v108, -v95, v107, v106
	v_fmac_f32_e32 v107, v108, v101
	v_fma_f32 v95, -v95, v107, v106
	v_div_fmas_f32 v95, v95, v101, v107
	v_div_fixup_f32 v40, v95, v40, v93
	v_pk_mul_f32 v[40:41], v[102:103], v[40:41]
	s_nop 0
	s_waitcnt lgkmcnt(0)
	v_mov_b32_e32 v102, v208
	v_mov_b32_e32 v103, v209
	v_lshlrev_b32_e32 v93, 16, v102
	v_mul_f32_e32 v93, 0xbfb8aa3b, v93
	v_exp_f32_e32 v106, v93
	v_and_b32_e32 v93, 0xffff0000, v102
	v_mul_f32_e32 v93, 0xbfb8aa3b, v93
	v_exp_f32_e32 v107, v93
	s_nop 0
	v_pk_add_f32 v[106:107], v[106:107], 1.0 op_sel_hi:[1,0]
	s_nop 0
	v_div_scale_f32 v93, s[0:1], v107, v107, 1.0
	v_rcp_f32_e32 v95, v93
	s_nop 0
	v_fma_f32 v101, -v93, v95, 1.0
	v_fmac_f32_e32 v95, v101, v95
	v_div_scale_f32 v101, vcc, 1.0, v107, 1.0
	v_mul_f32_e32 v102, v101, v95
	v_fma_f32 v108, -v93, v102, v101
	v_fmac_f32_e32 v102, v108, v95
	v_fma_f32 v93, -v93, v102, v101
	v_div_fmas_f32 v93, v93, v95, v102
	v_div_fixup_f32 v107, v93, v107, 1.0
	v_div_scale_f32 v93, s[0:1], v106, v106, 1.0
	v_rcp_f32_e32 v95, v93
	s_nop 0
	v_fma_f32 v101, -v93, v95, 1.0
	v_fmac_f32_e32 v95, v101, v95
	v_div_scale_f32 v101, vcc, 1.0, v106, 1.0
	v_mul_f32_e32 v102, v101, v95
	v_fma_f32 v108, -v93, v102, v101
	v_fmac_f32_e32 v102, v108, v95
	v_fma_f32 v93, -v93, v102, v101
	v_div_fmas_f32 v93, v93, v95, v102
	v_div_fixup_f32 v106, v93, v106, 1.0
	v_lshlrev_b32_e32 v93, 16, v103
	v_mul_f32_e32 v93, 0xbfb8aa3b, v93
	v_exp_f32_e32 v102, v93
	v_and_b32_e32 v93, 0xffff0000, v103
	v_mul_f32_e32 v93, 0xbfb8aa3b, v93
	v_exp_f32_e32 v103, v93
	v_pk_mul_f32 v[42:43], v[42:43], v[106:107]
	v_pk_add_f32 v[102:103], v[102:103], 1.0 op_sel_hi:[1,0]
	s_nop 0
	v_div_scale_f32 v93, s[0:1], v103, v103, 1.0
	v_rcp_f32_e32 v95, v93
	v_cvt_pk_bf16_f32 v42, v42, v43
	v_fma_f32 v101, -v93, v95, 1.0
	v_fmac_f32_e32 v95, v101, v95
	v_div_scale_f32 v101, vcc, 1.0, v103, 1.0
	v_mul_f32_e32 v106, v101, v95
	v_fma_f32 v107, -v93, v106, v101
	v_fmac_f32_e32 v106, v107, v95
	v_fma_f32 v93, -v93, v106, v101
	v_div_fmas_f32 v93, v93, v95, v106
	v_div_fixup_f32 v103, v93, v103, 1.0
	v_div_scale_f32 v93, s[0:1], v102, v102, 1.0
	v_rcp_f32_e32 v95, v93
	s_nop 0
	v_fma_f32 v101, -v93, v95, 1.0
	v_fmac_f32_e32 v95, v101, v95
	v_div_scale_f32 v101, vcc, 1.0, v102, 1.0
	v_mul_f32_e32 v106, v101, v95
	v_fma_f32 v107, -v93, v106, v101
	v_fmac_f32_e32 v106, v107, v95
	v_fma_f32 v93, -v93, v106, v101
	v_div_fmas_f32 v93, v93, v95, v106
	v_div_fixup_f32 v102, v93, v102, 1.0
	v_pk_mul_f32 v[40:41], v[40:41], v[102:103]
	s_nop 0
	v_cvt_pk_bf16_f32 v43, v40, v41
	global_store_dwordx2 v[72:73], v[42:43], off
	s_nop 0
	s_nop 0
	s_nop 0
	s_waitcnt lgkmcnt(0)
; DI size_t kblk(int row, int col, int nrows) { return ((size_t)(col >> 5) * nrows + row) * 32 + (col & 31); }
; DI unsigned pk2(float a, float b) { hwf32x2 f = {a, b}; hwbf16x2 r = __builtin_convertvector(f, hwbf16x2); return __builtin_bit_cast(unsigned, r); }
; DI float sigmoidf_(float z) { return 1.f / (1.f + __expf(-z)); }
; DI float siluf_(float z) { return z / (1.f + __expf(-z)); }
; template <int MX, bool OUT>
; DI void rec_chunk(const Params& p, int l, int b, int h, int dir, int T0, unsigned char* smem, f32x4 (&St)[4], float& nst, float& dtot, int tid, const RecRaw& raw) {
;     ...
;       for (int a = 0; a < 4; ++a) {
;         const int v0 = 16 * a + 4 * g;
;         const uint2 gt = *(const uint2*)(prow + GATE + cb + v0);
;         const float4 gg = *(const float4*)(gvec + v0);
;         float y0 = O[a][0] * rstd * gg.x * siluf_(__uint_as_float(gt.x << 16));
;         float y1 = O[a][1] * rstd * gg.y * siluf_(__uint_as_float(gt.x & 0xffff0000u));
;         float y2 = O[a][2] * rstd * gg.z * siluf_(__uint_as_float(gt.y << 16));
;         float y3 = O[a][3] * rstd * gg.w * siluf_(__uint_as_float(gt.y & 0xffff0000u));
;         if (MX == 1) {
;           const uint2 og = *(const uint2*)(prow + D_OG + h * 64 + v0);
;           y0 *= sigmoidf_(__uint_as_float(og.x << 16)); y1 *= sigmoidf_(__uint_as_float(og.x & 0xffff0000u));
;           y2 *= sigmoidf_(__uint_as_float(og.y << 16)); y3 *= sigmoidf_(__uint_as_float(og.y & 0xffff0000u));
;         }
;         *(uint2*)(MIX + kblk((int)orow, cb + v0, ROWS)) = make_uint2(pk2(y0, y1), pk2(y2, y3));
	v_mov_b32_e32 v40, v204
	v_mov_b32_e32 v41, v205
	v_mov_b32_e32 v74, v199
	v_mov_b32_e32 v75, v210
	v_lshlrev_b32_e32 v73, 16, v40
	v_and_b32_e32 v93, 0xffff0000, v40
	v_lshlrev_b32_e32 v40, 16, v41
	v_mul_f32_e32 v42, 0xbfb8aa3b, v40
	v_exp_f32_e32 v42, v42
	s_nop 0
	v_add_f32_e32 v42, 1.0, v42
	v_div_scale_f32 v43, s[0:1], v42, v42, v40
	v_rcp_f32_e32 v72, v43
	s_nop 0
	v_fma_f32 v95, -v43, v72, 1.0
	v_fmac_f32_e32 v72, v95, v72
	v_div_scale_f32 v95, vcc, v40, v42, v40
	v_mul_f32_e32 v101, v95, v72
	v_fma_f32 v102, -v43, v101, v95
	v_fmac_f32_e32 v101, v102, v72
	v_fma_f32 v43, -v43, v101, v95
	v_div_fmas_f32 v43, v43, v72, v101
	v_and_b32_e32 v95, 0xffff0000, v41
	v_div_fixup_f32 v72, v43, v42, v40
	v_mul_f32_e32 v40, 0xbfb8aa3b, v95
	v_exp_f32_e32 v102, v40
	v_lshlrev_b32_e32 v40, 16, v74
	v_mul_f32_e32 v40, 0xbfb8aa3b, v40
	v_exp_f32_e32 v104, v40
	v_and_b32_e32 v40, 0xffff0000, v74
	v_mul_f32_e32 v40, 0xbfb8aa3b, v40
	v_exp_f32_e32 v105, v40
	global_load_dwordx4 v[40:43], v[88:89], off offset:192
	v_pk_mul_f32 v[70:71], v[70:71], v[100:101] op_sel_hi:[1,0]
	v_mul_f32_e32 v74, 0xbfb8aa3b, v73
	v_exp_f32_e32 v106, v74
	s_waitcnt vmcnt(0)
	v_pk_mul_f32 v[40:41], v[70:71], v[40:41]
	v_mul_f32_e32 v70, 0xbfb8aa3b, v93
	v_exp_f32_e32 v107, v70
	s_nop 0
	v_pk_add_f32 v[70:71], v[106:107], 1.0 op_sel_hi:[1,0]
	s_nop 0
	v_div_scale_f32 v74, s[0:1], v71, v71, v93
	v_rcp_f32_e32 v101, v74
	s_nop 0
	v_fma_f32 v103, -v74, v101, 1.0
	v_fmac_f32_e32 v101, v103, v101
	v_div_scale_f32 v103, vcc, v93, v71, v93
	v_mul_f32_e32 v106, v103, v101
	v_fma_f32 v107, -v74, v106, v103
	v_fmac_f32_e32 v106, v107, v101
	v_fma_f32 v74, -v74, v106, v103
	v_div_fmas_f32 v74, v74, v101, v106
	v_div_fixup_f32 v71, v74, v71, v93
	v_div_scale_f32 v74, s[0:1], v70, v70, v73
	v_rcp_f32_e32 v93, v74
	s_nop 0
	v_fma_f32 v101, -v74, v93, 1.0
	v_fmac_f32_e32 v93, v101, v93
	v_div_scale_f32 v101, vcc, v73, v70, v73
	v_mul_f32_e32 v103, v101, v93
	v_fma_f32 v106, -v74, v103, v101
	v_fmac_f32_e32 v103, v106, v93
	v_fma_f32 v74, -v74, v103, v101
	v_div_fmas_f32 v74, v74, v93, v103
	v_div_fixup_f32 v70, v74, v70, v73
	v_pk_mul_f32 v[40:41], v[40:41], v[70:71]
	v_pk_add_f32 v[70:71], v[104:105], 1.0 op_sel_hi:[1,0]
	s_nop 0
	v_div_scale_f32 v73, s[0:1], v71, v71, 1.0
	v_rcp_f32_e32 v74, v73
	s_nop 0
	v_fma_f32 v93, -v73, v74, 1.0
	v_fmac_f32_e32 v74, v93, v74
	v_div_scale_f32 v93, vcc, 1.0, v71, 1.0
	v_mul_f32_e32 v101, v93, v74
	v_fma_f32 v103, -v73, v101, v93
	v_fmac_f32_e32 v101, v103, v74
	v_fma_f32 v73, -v73, v101, v93
	v_div_fmas_f32 v73, v73, v74, v101
	v_div_fixup_f32 v71, v73, v71, 1.0
	v_div_scale_f32 v73, s[0:1], v70, v70, 1.0
	v_rcp_f32_e32 v74, v73
	s_nop 0
	v_fma_f32 v93, -v73, v74, 1.0
	v_fmac_f32_e32 v74, v93, v74
	v_div_scale_f32 v93, vcc, 1.0, v70, 1.0
	v_mul_f32_e32 v101, v93, v74
	v_fma_f32 v103, -v73, v101, v93
	v_fmac_f32_e32 v101, v103, v74
	v_fma_f32 v73, -v73, v101, v93
	v_div_fmas_f32 v73, v73, v74, v101
	v_div_fixup_f32 v70, v73, v70, 1.0
	v_pk_mul_f32 v[40:41], v[40:41], v[70:71]
	v_lshlrev_b32_e32 v70, 16, v75
	v_mul_f32_e32 v70, 0xbfb8aa3b, v70
	v_exp_f32_e32 v70, v70
	v_cvt_pk_bf16_f32 v40, v40, v41
	v_add_f32_e32 v70, 1.0, v70
	v_div_scale_f32 v71, s[0:1], v70, v70, 1.0
	v_rcp_f32_e32 v73, v71
	s_nop 0
	v_fma_f32 v74, -v71, v73, 1.0
	v_fmac_f32_e32 v73, v74, v73
	v_div_scale_f32 v74, vcc, 1.0, v70, 1.0
	v_mul_f32_e32 v93, v74, v73
	v_fma_f32 v101, -v71, v93, v74
	v_fmac_f32_e32 v93, v101, v73
	v_fma_f32 v71, -v71, v93, v74
	v_div_fmas_f32 v71, v71, v73, v93
	v_div_fixup_f32 v70, v71, v70, 1.0
	v_and_b32_e32 v71, 0xffff0000, v75
	v_mul_f32_e32 v71, 0xbfb8aa3b, v71
	v_exp_f32_e32 v103, v71
	s_nop 0
	v_pk_add_f32 v[74:75], v[102:103], 1.0 op_sel_hi:[1,0]
	s_nop 0
	v_div_scale_f32 v71, s[0:1], v75, v75, 1.0
	v_rcp_f32_e32 v73, v71
	s_nop 0
	v_fma_f32 v93, -v71, v73, 1.0
	v_fmac_f32_e32 v73, v93, v73
	v_div_scale_f32 v93, vcc, 1.0, v75, 1.0
	v_mul_f32_e32 v101, v93, v73
	v_fma_f32 v102, -v71, v101, v93
	v_fmac_f32_e32 v101, v102, v73
	v_fma_f32 v71, -v71, v101, v93
	v_div_fmas_f32 v71, v71, v73, v101
	v_div_scale_f32 v73, s[0:1], v74, v74, v95
	v_div_fixup_f32 v71, v71, v75, 1.0
	v_rcp_f32_e32 v75, v73
	s_mov_b64 s[0:1], 0
	v_fma_f32 v93, -v73, v75, 1.0
	v_fmac_f32_e32 v75, v93, v75
	v_div_scale_f32 v93, vcc, v95, v74, v95
	v_mul_f32_e32 v101, v93, v75
	v_fma_f32 v102, -v73, v101, v93
	v_fmac_f32_e32 v101, v102, v75
	v_fma_f32 v73, -v73, v101, v93
	v_div_fmas_f32 v73, v73, v75, v101
	v_pk_mul_f32 v[68:69], v[68:69], v[100:101] op_sel_hi:[1,0]
	v_div_fixup_f32 v73, v73, v74, v95
	v_pk_mul_f32 v[42:43], v[68:69], v[42:43]
	v_mov_b32_e32 v95, v161
	v_pk_mul_f32 v[42:43], v[42:43], v[72:73]
	v_lshl_add_u64 v[66:67], v[66:67], 0, v[94:95]
	v_pk_mul_f32 v[42:43], v[42:43], v[70:71]
	global_store_dword v[66:67], v40, off

; DI size_t kblk(int row, int col, int nrows) { return ((size_t)(col >> 5) * nrows + row) * 32 + (col & 31); }
; DI unsigned pk2(float a, float b) { hwf32x2 f = {a, b}; hwbf16x2 r = __builtin_convertvector(f, hwbf16x2); return __builtin_bit_cast(unsigned, r); }
; #define MFMA16(a, b, c) __builtin_amdgcn_mfma_f32_16x16x32_bf16((a), (b), (c), 0, 0, 0)
; template <int MX, bool OUT>
; DI void rec_chunk(const Params& p, int l, int b, int h, int dir, int T0, unsigned char* smem, f32x4 (&St)[4], float& nst, float& dtot, int tid, const RecRaw& raw) {
;     ...
; #pragma unroll
;     for (int ks = 0; ks < 2; ++ks) {
;       const bf16x8 fb = *(const bf16x8*)(smem + L_QS + swz(t, ks * 4 + g));
; #pragma unroll
;       for (int a = 0; a < 4; ++a) {
;         const bf16x8 fa = *(const bf16x8*)(smem + L_STT + swz(16 * a + col, ks * 4 + g));
;         O[a] = MFMA16(fa, fb, O[a]);
;       }
;     }
;     if (MX == 1) {
;       const float inv = 1.f / fmaxf(fabsf(den), 1.f);
; #pragma unroll
;       for (int a = 0; a < 4; ++a)
; #pragma unroll
;         for (int j = 0; j < 4; ++j) O[a][j] *= inv;
;     }
;     if (dir == 0) {
; #pragma unroll
;       for (int a = 0; a < 4; ++a) *(uint2*)(MIX + kblk((int)orow, cb + 16 * a + 4 * g, ROWS)) = make_uint2(pk2(O[a][0], O[a][1]), pk2(O[a][2], O[a][3]));
;     } else {
;       float ss = 0.f;
; #pragma unroll
;       for (int a = 0; a < 4; ++a) {
;         const uint2 u = *(const uint2*)(MIX + kblk((int)orow, cb + 16 * a + 4 * g, ROWS));
;         O[a][0] += __uint_as_float(u.x << 16); O[a][1] += __uint_as_float(u.x & 0xffff0000u);
;         O[a][2] += __uint_as_float(u.y << 16); O[a][3] += __uint_as_float(u.y & 0xffff0000u);
; #pragma unroll
;         for (int j = 0; j < 4; ++j) ss += O[a][j] * O[a][j];
;       }
;       ss += __shfl_xor(ss, 16);
;       ss += __shfl_xor(ss, 32);
;       const float rstd = rsqrtf(ss * (1.f / 64.f) + EPS);
;       const float* gvec = (MX ? p.ml_g : p.hg_g) + l * 64;
; #pragma unroll
;       for (int a = 0; a < 4; ++a) {
;         const int v0 = 16 * a + 4 * g;
;         const uint2 gt = *(const uint2*)(prow + GATE + cb + v0);
.LBB0_1014:
	s_or_b64 exec, exec, s[26:27]
	s_add_i32 s26, s83, -1
	v_mov_b32_e32 v40, s26
	v_cndmask_b32_e64 v40, v95, v40, s[8:9]
	v_lshlrev_b32_e32 v40, 6, v40
	v_add_u32_e32 v40, s81, v40
	v_mov_b32_e32 v41, v161
	v_lshl_add_u64 v[68:69], v[40:41], 0, v[84:85]
	ds_read_b128 v[40:43], v203 offset:32768
	ds_read_b128 v[44:47], v201 offset:57344
	ds_read_b128 v[48:51], v201 offset:59392
	ds_read_b128 v[52:55], v201 offset:61440
	s_waitcnt lgkmcnt(0)
	v_mfma_f32_16x16x32_bf16 v[44:47], v[44:47], v[40:43], v[56:59]
	s_mov_b64 s[26:27], -1
	s_nop 1
	ds_read_b128 v[56:59], v201 offset:63488
	s_and_b64 vcc, exec, s[78:79]
	v_mfma_f32_16x16x32_bf16 v[48:51], v[48:51], v[40:43], v[60:63]
	v_ashrrev_i32_e32 v204, 31, v68
	v_mfma_f32_16x16x32_bf16 v[52:55], v[52:55], v[40:43], v[64:67]
	s_waitcnt lgkmcnt(0)
	v_mfma_f32_16x16x32_bf16 v[56:59], v[56:59], v[40:43], v[72:75]
	ds_read_b128 v[60:63], v202 offset:32768
	ds_read_b128 v[40:43], v200 offset:57344
	s_waitcnt lgkmcnt(0)
	v_mfma_f32_16x16x32_bf16 v[40:43], v[40:43], v[60:63], v[44:47]
	s_nop 2
	ds_read_b128 v[44:47], v200 offset:59392
	s_waitcnt lgkmcnt(0)
	v_mfma_f32_16x16x32_bf16 v[48:51], v[44:47], v[60:63], v[48:51]
	ds_read_b128 v[44:47], v200 offset:61440
	s_waitcnt lgkmcnt(0)
	v_mfma_f32_16x16x32_bf16 v[52:55], v[44:47], v[60:63], v[52:55]
	ds_read_b128 v[44:47], v200 offset:63488
	s_waitcnt lgkmcnt(0)
	v_mfma_f32_16x16x32_bf16 v[44:47], v[44:47], v[60:63], v[56:59]
	s_cbranch_vccnz .LBB0_1016
	s_nop 1
	v_mov_b64_e32 v[56:57], s[14:15]
	v_mad_u64_u32 v[56:57], s[26:27], v68, s33, v[56:57]
	v_mad_i32_i24 v57, v69, s33, v57
	v_mov_b32_e32 v69, v204
	v_lshl_add_u64 v[60:61], v[68:69], 0, s[30:31]
	v_lshlrev_b64 v[60:61], 6, v[60:61]
	v_lshl_add_u64 v[70:71], v[90:91], 0, v[60:61]
	global_load_dwordx2 v[60:61], v[70:71], off
	v_lshl_add_u64 v[58:59], v[68:69], 0, s[28:29]
	v_lshlrev_b64 v[58:59], 6, v[58:59]
	v_mov_b32_e32 v95, v161
	v_lshl_add_u64 v[100:101], v[86:87], 0, v[58:59]
	global_load_dwordx2 v[58:59], v[100:101], off
	s_mov_b64 s[26:27], 0x41c7a20
	v_lshl_add_u64 v[56:57], v[56:57], 0, s[26:27]
	v_lshl_add_u64 v[72:73], v[56:57], 0, s[2:3]
	v_lshl_add_u64 v[56:57], v[56:57], 0, v[94:95]
	v_lshl_add_u64 v[56:57], v[56:57], 0, s[2:3]
	v_cmp_lt_i32_e32 vcc, v183, v178
	v_lshl_add_u64 v[72:73], v[72:73], 0, v[94:95]
	global_load_dwordx4 v[228:231], v[88:89], off
	global_load_dwordx4 v[232:235], v[88:89], off offset:64
	global_load_dwordx4 v[236:239], v[88:89], off offset:128
	global_load_dwordx4 v[240:243], v[88:89], off offset:192
	global_load_dwordx2 v[226:227], v[72:73], off offset:32
	global_load_dwordx2 v[244:245], v[72:73], off offset:64
	global_load_dwordx2 v[246:247], v[72:73], off offset:96
	global_load_dwordx2 v[56:57], v[56:57], off
	s_waitcnt vmcnt(0) lgkmcnt(0)
	v_lshlrev_b32_e32 v74, 16, v60
	v_and_b32_e32 v75, 0xffff0000, v60
	v_lshlrev_b32_e32 v102, 16, v61
	v_and_b32_e32 v103, 0xffff0000, v61
	v_lshl_add_u64 v[60:61], v[68:69], 0, s[42:43]
	v_lshlrev_b64 v[60:61], 6, v[60:61]
	v_lshl_add_u64 v[60:61], s[6:7], 0, v[60:61]
	v_lshl_add_u64 v[66:67], v[60:61], 0, v[94:95]
	global_load_dwordx2 v[248:249], v[66:67], off
	global_load_dwordx2 v[250:251], v[66:67], off offset:32
	s_nop 0
	v_cndmask_b32_e32 v69, v177, v183, vcc
	v_cmp_lt_i32_e32 vcc, v184, v178
	v_lshlrev_b32_e32 v97, 2, v69
	v_lshlrev_b32_e32 v116, 16, v58
	v_cndmask_b32_e32 v69, v177, v184, vcc
	v_and_b32_e32 v117, 0xffff0000, v58
	v_lshlrev_b32_e32 v58, 16, v59
	v_and_b32_e32 v59, 0xffff0000, v59
	v_pk_add_f32 v[112:113], v[42:43], v[58:59]
	v_pk_add_f32 v[116:117], v[40:41], v[116:117]
	v_pk_mul_f32 v[114:115], v[112:113], v[112:113]
	v_pk_mul_f32 v[120:121], v[116:117], v[116:117]
	v_lshlrev_b32_e32 v69, 2, v69
	v_add_f32_e32 v95, v120, v121
	v_add_f32_e32 v95, v95, v114
	v_add_f32_e32 v95, v115, v95
	v_lshlrev_b32_e32 v205, 16, v56
	v_and_b32_e32 v206, 0xffff0000, v56
	v_lshlrev_b32_e32 v208, 16, v57
	v_and_b32_e32 v209, 0xffff0000, v57
	s_nop 0
	v_mul_f32_e32 v118, 0xbfb8aa3b, v205
	v_mul_f32_e32 v119, 0xbfb8aa3b, v206
	v_exp_f32_e32 v118, v118
	v_exp_f32_e32 v119, v119
	s_waitcnt vmcnt(0) lgkmcnt(0)
	v_mov_b32_e32 v62, v248
	v_mov_b32_e32 v63, v249
	v_mov_b32_e32 v56, v228
	v_mov_b32_e32 v57, v229
	v_mov_b32_e32 v58, v230
	v_mov_b32_e32 v59, v231
	v_lshlrev_b32_e32 v108, 16, v62
	v_and_b32_e32 v109, 0xffff0000, v62
	v_lshlrev_b32_e32 v110, 16, v63
	v_and_b32_e32 v111, 0xffff0000, v63
	s_nop 0
	v_pk_add_f32 v[118:119], v[118:119], 1.0 op_sel_hi:[1,0]
	v_pk_add_f32 v[108:109], v[52:53], v[108:109]
	v_div_scale_f32 v207, s[26:27], v119, v119, v206
	v_rcp_f32_e32 v210, v207
	v_pk_mul_f32 v[214:215], v[108:109], v[108:109]
	v_fma_f32 v211, -v207, v210, 1.0
	v_fmac_f32_e32 v210, v211, v210
	v_div_scale_f32 v211, vcc, v206, v119, v206
	v_mul_f32_e32 v212, v211, v210
	v_fma_f32 v213, -v207, v212, v211
	v_fmac_f32_e32 v212, v213, v210
	v_fma_f32 v207, -v207, v212, v211
	v_div_fmas_f32 v207, v207, v210, v212
	v_div_fixup_f32 v119, v207, v119, v206
	v_div_scale_f32 v206, s[26:27], v118, v118, v205
	v_rcp_f32_e32 v207, v206
	s_waitcnt lgkmcnt(0)
; DI size_t kblk(int row, int col, int nrows) { return ((size_t)(col >> 5) * nrows + row) * 32 + (col & 31); }
; DI unsigned pk2(float a, float b) { hwf32x2 f = {a, b}; hwbf16x2 r = __builtin_convertvector(f, hwbf16x2); return __builtin_bit_cast(unsigned, r); }
; DI float sigmoidf_(float z) { return 1.f / (1.f + __expf(-z)); }
; DI float siluf_(float z) { return z / (1.f + __expf(-z)); }
; template <int MX, bool OUT>
; DI void rec_chunk(const Params& p, int l, int b, int h, int dir, int T0, unsigned char* smem, f32x4 (&St)[4], float& nst, float& dtot, int tid, const RecRaw& raw) {
;     ...
;       float ss = 0.f;
; #pragma unroll
;       for (int a = 0; a < 4; ++a) {
;         const uint2 u = *(const uint2*)(MIX + kblk((int)orow, cb + 16 * a + 4 * g, ROWS));
;         O[a][0] += __uint_as_float(u.x << 16); O[a][1] += __uint_as_float(u.x & 0xffff0000u);
;         O[a][2] += __uint_as_float(u.y << 16); O[a][3] += __uint_as_float(u.y & 0xffff0000u);
; #pragma unroll
;         for (int j = 0; j < 4; ++j) ss += O[a][j] * O[a][j];
;       }
;       ss += __shfl_xor(ss, 16);
;       ss += __shfl_xor(ss, 32);
;       const float rstd = rsqrtf(ss * (1.f / 64.f) + EPS);
;       const float* gvec = (MX ? p.ml_g : p.hg_g) + l * 64;
; #pragma unroll
;       for (int a = 0; a < 4; ++a) {
;         const int v0 = 16 * a + 4 * g;
;         const uint2 gt = *(const uint2*)(prow + GATE + cb + v0);
;         const float4 gg = *(const float4*)(gvec + v0);
;         float y0 = O[a][0] * rstd * gg.x * siluf_(__uint_as_float(gt.x << 16));
;         float y1 = O[a][1] * rstd * gg.y * siluf_(__uint_as_float(gt.x & 0xffff0000u));
;         float y2 = O[a][2] * rstd * gg.z * siluf_(__uint_as_float(gt.y << 16));
;         float y3 = O[a][3] * rstd * gg.w * siluf_(__uint_as_float(gt.y & 0xffff0000u));
;         if (MX == 1) {
;           const uint2 og = *(const uint2*)(prow + D_OG + h * 64 + v0);
;           y0 *= sigmoidf_(__uint_as_float(og.x << 16)); y1 *= sigmoidf_(__uint_as_float(og.x & 0xffff0000u));
;           y2 *= sigmoidf_(__uint_as_float(og.y << 16)); y3 *= sigmoidf_(__uint_as_float(og.y & 0xffff0000u));
;         }
;         *(uint2*)(MIX + kblk((int)orow, cb + v0, ROWS)) = make_uint2(pk2(y0, y1), pk2(y2, y3));
	v_mov_b32_e32 v62, v250
	v_mov_b32_e32 v63, v251
	v_lshlrev_b32_e32 v64, 16, v62
	v_fma_f32 v210, -v206, v207, 1.0
	v_fmac_f32_e32 v207, v210, v207
	v_div_scale_f32 v210, vcc, v205, v118, v205
	v_mul_f32_e32 v211, v210, v207
	v_fma_f32 v212, -v206, v211, v210
	v_fmac_f32_e32 v211, v212, v207
	v_fma_f32 v206, -v206, v211, v210
	v_div_fmas_f32 v206, v206, v207, v211
	v_div_fixup_f32 v118, v206, v118, v205
	v_mul_f32_e32 v205, 0xbfb8aa3b, v208
	v_exp_f32_e32 v206, v205
	v_mul_f32_e32 v205, 0xbfb8aa3b, v209
	v_exp_f32_e32 v207, v205
	v_and_b32_e32 v65, 0xffff0000, v62
	v_pk_add_f32 v[64:65], v[44:45], v[64:65]
	v_lshlrev_b32_e32 v62, 16, v63
	v_pk_add_f32 v[206:207], v[206:207], 1.0 op_sel_hi:[1,0]
	v_and_b32_e32 v63, 0xffff0000, v63
	v_div_scale_f32 v205, s[26:27], v207, v207, v209
	v_rcp_f32_e32 v210, v205
	v_pk_mul_f32 v[104:105], v[64:65], v[64:65]
	v_pk_add_f32 v[62:63], v[46:47], v[62:63]
	v_fma_f32 v211, -v205, v210, 1.0
	v_fmac_f32_e32 v210, v211, v210
	v_div_scale_f32 v211, vcc, v209, v207, v209
	v_mul_f32_e32 v212, v211, v210
	v_fma_f32 v213, -v205, v212, v211
	v_fmac_f32_e32 v212, v213, v210
	v_fma_f32 v205, -v205, v212, v211
	v_div_fmas_f32 v205, v205, v210, v212
	v_div_fixup_f32 v207, v205, v207, v209
	v_div_scale_f32 v205, s[26:27], v206, v206, v208
	v_rcp_f32_e32 v209, v205
	v_pk_mul_f32 v[106:107], v[62:63], v[62:63]
	v_fma_f32 v210, -v205, v209, 1.0
	v_fmac_f32_e32 v209, v210, v209
	v_div_scale_f32 v210, vcc, v208, v206, v208
	v_mul_f32_e32 v211, v210, v209
	v_fma_f32 v212, -v205, v211, v210
	v_fmac_f32_e32 v211, v212, v209
	v_fma_f32 v205, -v205, v211, v210
	v_pk_add_f32 v[212:213], v[48:49], v[74:75]
	v_div_fmas_f32 v205, v205, v209, v211
	v_pk_mul_f32 v[74:75], v[212:213], v[212:213]
	v_div_fixup_f32 v206, v205, v206, v208
	v_pk_add_f32 v[208:209], v[50:51], v[102:103]
	v_add_f32_e32 v74, v74, v95
	v_pk_mul_f32 v[210:211], v[208:209], v[208:209]
	v_add_f32_e32 v74, v75, v74
	v_add_f32_e32 v74, v210, v74
	v_add_f32_e32 v74, v211, v74
	v_pk_add_f32 v[102:103], v[54:55], v[110:111]
	v_add_f32_e32 v74, v214, v74
	v_pk_mul_f32 v[110:111], v[102:103], v[102:103]
	v_add_f32_e32 v74, v215, v74
	v_add_f32_e32 v74, v110, v74
	v_add_f32_e32 v74, v111, v74
	v_add_f32_e32 v74, v104, v74
	v_add_f32_e32 v74, v105, v74
	v_add_f32_e32 v74, v106, v74
	v_add_f32_e32 v74, v107, v74
	ds_bpermute_b32 v75, v97, v74
	s_waitcnt lgkmcnt(0)
	v_add_f32_e32 v74, v74, v75
	ds_bpermute_b32 v69, v69, v74
	s_waitcnt lgkmcnt(0)
	v_add_f32_e32 v69, v74, v69
	v_fmamk_f32 v69, v69, 0x3c800000, v162
	v_cmp_gt_f32_e32 vcc, s38, v69
	v_mul_f32_e32 v74, 0x4b800000, v69
	s_nop 0
	v_cndmask_b32_e32 v69, v69, v74, vcc
	v_rsq_f32_e32 v69, v69
	s_nop 0
	v_mul_f32_e32 v74, 0x45800000, v69
	v_cndmask_b32_e32 v74, v69, v74, vcc
	v_pk_mul_f32 v[104:105], v[116:117], v[74:75] op_sel_hi:[1,0]
	s_nop 0
	v_pk_mul_f32 v[56:57], v[56:57], v[104:105]
	v_pk_mul_f32 v[104:105], v[112:113], v[74:75] op_sel_hi:[1,0]
	v_pk_mul_f32 v[56:57], v[118:119], v[56:57]
	v_pk_mul_f32 v[58:59], v[58:59], v[104:105]
	v_cvt_pk_bf16_f32 v56, v56, v57
	v_pk_mul_f32 v[58:59], v[206:207], v[58:59]
	s_nop 0
	v_cvt_pk_bf16_f32 v57, v58, v59
	global_store_dwordx2 v[100:101], v[56:57], off
	s_nop 0
	s_nop 0
	s_nop 0
	s_waitcnt lgkmcnt(0)
	v_mov_b32_e32 v100, v226
	v_mov_b32_e32 v101, v227
	v_mov_b32_e32 v56, v232
	v_mov_b32_e32 v57, v233
	v_mov_b32_e32 v58, v234
	v_mov_b32_e32 v59, v235
	v_lshlrev_b32_e32 v69, 16, v100
	v_and_b32_e32 v75, 0xffff0000, v100
	v_mul_f32_e32 v95, 0xbfb8aa3b, v69
	v_exp_f32_e32 v104, v95
	v_mul_f32_e32 v95, 0xbfb8aa3b, v75
	v_exp_f32_e32 v105, v95
	v_pk_mul_f32 v[106:107], v[212:213], v[74:75] op_sel_hi:[1,0]
	v_pk_add_f32 v[104:105], v[104:105], 1.0 op_sel_hi:[1,0]
	s_nop 0
	v_div_scale_f32 v95, s[26:27], v105, v105, v75
	v_rcp_f32_e32 v97, v95
	v_pk_mul_f32 v[56:57], v[56:57], v[106:107]
	v_fma_f32 v100, -v95, v97, 1.0
	v_fmac_f32_e32 v97, v100, v97
	v_div_scale_f32 v100, vcc, v75, v105, v75
	v_mul_f32_e32 v106, v100, v97
	v_fma_f32 v107, -v95, v106, v100
	v_fmac_f32_e32 v106, v107, v97
	v_fma_f32 v95, -v95, v106, v100
	v_div_fmas_f32 v95, v95, v97, v106
	v_div_fixup_f32 v105, v95, v105, v75
	v_div_scale_f32 v75, s[26:27], v104, v104, v69
	v_rcp_f32_e32 v95, v75
	s_nop 0
	v_fma_f32 v97, -v75, v95, 1.0
	v_fmac_f32_e32 v95, v97, v95
	v_div_scale_f32 v97, vcc, v69, v104, v69
	v_mul_f32_e32 v100, v97, v95
	v_fma_f32 v106, -v75, v100, v97
	v_fmac_f32_e32 v100, v106, v95
	v_fma_f32 v75, -v75, v100, v97
	v_div_fmas_f32 v75, v75, v95, v100
	v_div_fixup_f32 v104, v75, v104, v69
	v_lshlrev_b32_e32 v69, 16, v101
	v_and_b32_e32 v75, 0xffff0000, v101
	v_mul_f32_e32 v95, 0xbfb8aa3b, v69
	v_exp_f32_e32 v100, v95
	v_mul_f32_e32 v95, 0xbfb8aa3b, v75
	v_exp_f32_e32 v101, v95
	v_pk_mul_f32 v[56:57], v[104:105], v[56:57]
	v_pk_mul_f32 v[104:105], v[208:209], v[74:75] op_sel_hi:[1,0]
	v_cvt_pk_bf16_f32 v56, v56, v57
	v_pk_add_f32 v[100:101], v[100:101], 1.0 op_sel_hi:[1,0]
	v_pk_mul_f32 v[58:59], v[58:59], v[104:105]
	v_div_scale_f32 v95, s[26:27], v101, v101, v75
	v_rcp_f32_e32 v97, v95
	s_nop 0
	v_fma_f32 v104, -v95, v97, 1.0
	v_fmac_f32_e32 v97, v104, v97
	v_div_scale_f32 v104, vcc, v75, v101, v75
	v_mul_f32_e32 v105, v104, v97
	v_fma_f32 v106, -v95, v105, v104
	v_fmac_f32_e32 v105, v106, v97
	v_fma_f32 v95, -v95, v105, v104
	v_div_fmas_f32 v95, v95, v97, v105
	v_div_fixup_f32 v101, v95, v101, v75
	v_div_scale_f32 v75, s[26:27], v100, v100, v69
	v_rcp_f32_e32 v95, v75
	s_nop 0
	v_fma_f32 v97, -v75, v95, 1.0
	v_fmac_f32_e32 v95, v97, v95
	v_div_scale_f32 v97, vcc, v69, v100, v69
	v_mul_f32_e32 v104, v97, v95
	v_fma_f32 v105, -v75, v104, v97
	v_fmac_f32_e32 v104, v105, v95
	v_fma_f32 v75, -v75, v104, v97
	v_div_fmas_f32 v75, v75, v95, v104
	v_div_fixup_f32 v100, v75, v100, v69
	v_pk_mul_f32 v[58:59], v[100:101], v[58:59]
	s_nop 0
	v_cvt_pk_bf16_f32 v57, v58, v59
	global_store_dwordx2 v[70:71], v[56:57], off
	s_nop 0
	s_nop 0
	s_nop 0
	s_waitcnt lgkmcnt(0)
; DI size_t kblk(int row, int col, int nrows) { return ((size_t)(col >> 5) * nrows + row) * 32 + (col & 31); }
; DI unsigned pk2(float a, float b) { hwf32x2 f = {a, b}; hwbf16x2 r = __builtin_convertvector(f, hwbf16x2); return __builtin_bit_cast(unsigned, r); }
; DI float sigmoidf_(float z) { return 1.f / (1.f + __expf(-z)); }
; DI float siluf_(float z) { return z / (1.f + __expf(-z)); }
; template <int MX, bool OUT>
; DI void rec_chunk(const Params& p, int l, int b, int h, int dir, int T0, unsigned char* smem, f32x4 (&St)[4], float& nst, float& dtot, int tid, const RecRaw& raw) {
;     ...
;       for (int a = 0; a < 4; ++a) {
;         const int v0 = 16 * a + 4 * g;
;         const uint2 gt = *(const uint2*)(prow + GATE + cb + v0);
;         const float4 gg = *(const float4*)(gvec + v0);
;         float y0 = O[a][0] * rstd * gg.x * siluf_(__uint_as_float(gt.x << 16));
;         float y1 = O[a][1] * rstd * gg.y * siluf_(__uint_as_float(gt.x & 0xffff0000u));
;         float y2 = O[a][2] * rstd * gg.z * siluf_(__uint_as_float(gt.y << 16));
;         float y3 = O[a][3] * rstd * gg.w * siluf_(__uint_as_float(gt.y & 0xffff0000u));
;         if (MX == 1) {
;           const uint2 og = *(const uint2*)(prow + D_OG + h * 64 + v0);
;           y0 *= sigmoidf_(__uint_as_float(og.x << 16)); y1 *= sigmoidf_(__uint_as_float(og.x & 0xffff0000u));
;           y2 *= sigmoidf_(__uint_as_float(og.y << 16)); y3 *= sigmoidf_(__uint_as_float(og.y & 0xffff0000u));
;         }
;         *(uint2*)(MIX + kblk((int)orow, cb + v0, ROWS)) = make_uint2(pk2(y0, y1), pk2(y2, y3));
	v_mov_b32_e32 v70, v244
	v_mov_b32_e32 v71, v245
	v_mov_b32_e32 v56, v236
	v_mov_b32_e32 v57, v237
	v_mov_b32_e32 v58, v238
	v_mov_b32_e32 v59, v239
	v_lshlrev_b32_e32 v69, 16, v70
	v_and_b32_e32 v70, 0xffff0000, v70
	v_mul_f32_e32 v75, 0xbfb8aa3b, v69
	v_exp_f32_e32 v100, v75
	v_pk_mul_f32 v[104:105], v[108:109], v[74:75] op_sel_hi:[1,0]
	v_mul_f32_e32 v75, 0xbfb8aa3b, v70
	v_exp_f32_e32 v101, v75
	v_pk_mul_f32 v[56:57], v[104:105], v[56:57]
	v_pk_add_f32 v[100:101], v[100:101], 1.0 op_sel_hi:[1,0]
	s_nop 0
	v_div_scale_f32 v75, s[26:27], v101, v101, v70
	v_rcp_f32_e32 v95, v75
	s_nop 0
	v_fma_f32 v97, -v75, v95, 1.0
	v_fmac_f32_e32 v95, v97, v95
	v_div_scale_f32 v97, vcc, v70, v101, v70
	v_mul_f32_e32 v104, v97, v95
	v_fma_f32 v105, -v75, v104, v97
	v_fmac_f32_e32 v104, v105, v95
	v_fma_f32 v75, -v75, v104, v97
	v_div_fmas_f32 v75, v75, v95, v104
	v_div_fixup_f32 v101, v75, v101, v70
	v_div_scale_f32 v70, s[26:27], v100, v100, v69
	v_rcp_f32_e32 v75, v70
	s_nop 0
	v_fma_f32 v95, -v70, v75, 1.0
	v_fmac_f32_e32 v75, v95, v75
	v_div_scale_f32 v95, vcc, v69, v100, v69
	v_mul_f32_e32 v97, v95, v75
	v_fma_f32 v104, -v70, v97, v95
	v_fmac_f32_e32 v97, v104, v75
	v_fma_f32 v70, -v70, v97, v95
	v_div_fmas_f32 v70, v70, v75, v97
	v_div_fixup_f32 v100, v70, v100, v69
	v_lshlrev_b32_e32 v69, 16, v71
	v_and_b32_e32 v75, 0xffff0000, v71
	v_mul_f32_e32 v70, 0xbfb8aa3b, v69
	v_mul_f32_e32 v71, 0xbfb8aa3b, v75
	v_exp_f32_e32 v70, v70
	v_exp_f32_e32 v71, v71
	v_pk_mul_f32 v[56:57], v[56:57], v[100:101]
	v_pk_mul_f32 v[100:101], v[102:103], v[74:75] op_sel_hi:[1,0]
	v_cvt_pk_bf16_f32 v56, v56, v57
	v_pk_add_f32 v[70:71], v[70:71], 1.0 op_sel_hi:[1,0]
	v_pk_mul_f32 v[58:59], v[100:101], v[58:59]
	v_div_scale_f32 v95, s[26:27], v71, v71, v75
	v_rcp_f32_e32 v97, v95
	s_nop 0
	v_fma_f32 v100, -v95, v97, 1.0
	v_fmac_f32_e32 v97, v100, v97
	v_div_scale_f32 v100, vcc, v75, v71, v75
	v_mul_f32_e32 v101, v100, v97
	v_fma_f32 v102, -v95, v101, v100
	v_fmac_f32_e32 v101, v102, v97
	v_fma_f32 v95, -v95, v101, v100
	v_div_fmas_f32 v95, v95, v97, v101
	v_div_fixup_f32 v71, v95, v71, v75
	v_div_scale_f32 v75, s[26:27], v70, v70, v69
	v_rcp_f32_e32 v95, v75
	s_nop 0
	v_fma_f32 v97, -v75, v95, 1.0
	v_fmac_f32_e32 v95, v97, v95
	v_div_scale_f32 v97, vcc, v69, v70, v69
	v_mul_f32_e32 v100, v97, v95
	v_fma_f32 v101, -v75, v100, v97
	v_fmac_f32_e32 v100, v101, v95
	v_fma_f32 v75, -v75, v100, v97
	v_div_fmas_f32 v75, v75, v95, v100
	v_div_fixup_f32 v70, v75, v70, v69
	v_pk_mul_f32 v[58:59], v[58:59], v[70:71]
	v_pk_mul_f32 v[64:65], v[64:65], v[74:75] op_sel_hi:[1,0]
	v_cvt_pk_bf16_f32 v57, v58, v59
	global_store_dwordx2 v[66:67], v[56:57], off
	s_nop 0
	v_mov_b32_e32 v97, v161
	s_nop 0
	s_waitcnt lgkmcnt(0)
	v_mov_b32_e32 v66, v246
	v_mov_b32_e32 v67, v247
	v_mov_b32_e32 v56, v240
	v_mov_b32_e32 v57, v241
	v_mov_b32_e32 v58, v242
	v_mov_b32_e32 v59, v243
	v_lshlrev_b32_e32 v69, 16, v66
	v_and_b32_e32 v66, 0xffff0000, v66
	v_mul_f32_e32 v70, 0xbfb8aa3b, v69
	v_pk_mul_f32 v[56:57], v[64:65], v[56:57]
	v_mul_f32_e32 v64, 0xbfb8aa3b, v66
	v_exp_f32_e32 v70, v70
	v_exp_f32_e32 v71, v64
	s_nop 0
	v_pk_add_f32 v[64:65], v[70:71], 1.0 op_sel_hi:[1,0]
	s_nop 0
	v_div_scale_f32 v70, s[26:27], v65, v65, v66
	v_rcp_f32_e32 v71, v70
	s_nop 0
	v_fma_f32 v72, -v70, v71, 1.0
	v_fmac_f32_e32 v71, v72, v71
	v_div_scale_f32 v72, vcc, v66, v65, v66
	v_mul_f32_e32 v73, v72, v71
	v_fma_f32 v75, -v70, v73, v72
	v_fmac_f32_e32 v73, v75, v71
	v_fma_f32 v70, -v70, v73, v72
	v_div_fmas_f32 v70, v70, v71, v73
	v_div_fixup_f32 v65, v70, v65, v66
	v_div_scale_f32 v66, s[26:27], v64, v64, v69
	v_rcp_f32_e32 v70, v66
	v_pk_mul_f32 v[62:63], v[62:63], v[74:75] op_sel_hi:[1,0]
	v_fma_f32 v71, -v66, v70, 1.0
	v_fmac_f32_e32 v70, v71, v70
	v_div_scale_f32 v71, vcc, v69, v64, v69
	v_mul_f32_e32 v72, v71, v70
	v_fma_f32 v73, -v66, v72, v71
	v_fmac_f32_e32 v72, v73, v70
	v_fma_f32 v66, -v66, v72, v71
	v_div_fmas_f32 v66, v66, v70, v72
	v_div_fixup_f32 v64, v66, v64, v69
	v_lshlrev_b32_e32 v66, 16, v67
	v_and_b32_e32 v67, 0xffff0000, v67
	v_pk_mul_f32 v[64:65], v[56:57], v[64:65]
	v_mul_f32_e32 v56, 0xbfb8aa3b, v66
	v_mul_f32_e32 v57, 0xbfb8aa3b, v67
	v_exp_f32_e32 v56, v56
	v_exp_f32_e32 v57, v57
	v_pk_mul_f32 v[58:59], v[62:63], v[58:59]
	v_pk_add_f32 v[56:57], v[56:57], 1.0 op_sel_hi:[1,0]
	s_nop 0
	v_div_scale_f32 v62, s[26:27], v57, v57, v67
	v_rcp_f32_e32 v63, v62
	s_nop 0
	v_fma_f32 v69, -v62, v63, 1.0
	v_fmac_f32_e32 v63, v69, v63
	v_div_scale_f32 v69, vcc, v67, v57, v67
	v_mul_f32_e32 v70, v69, v63
	v_fma_f32 v71, -v62, v70, v69
	v_fmac_f32_e32 v70, v71, v63
	v_fma_f32 v62, -v62, v70, v69
	v_div_fmas_f32 v62, v62, v63, v70
	v_div_fixup_f32 v57, v62, v57, v67
	v_div_scale_f32 v62, s[26:27], v56, v56, v66
	v_rcp_f32_e32 v63, v62
	s_mov_b64 s[26:27], 0
	v_fma_f32 v67, -v62, v63, 1.0
	v_fmac_f32_e32 v63, v67, v63
	v_div_scale_f32 v67, vcc, v66, v56, v66
	v_mul_f32_e32 v69, v67, v63
	v_fma_f32 v70, -v62, v69, v67
	v_fmac_f32_e32 v69, v70, v63
	v_fma_f32 v62, -v62, v69, v67
	v_div_fmas_f32 v62, v62, v63, v69
	v_div_fixup_f32 v56, v62, v56, v66
	v_pk_mul_f32 v[56:57], v[58:59], v[56:57]
	v_cvt_pk_bf16_f32 v62, v64, v65
	v_lshl_add_u64 v[58:59], v[60:61], 0, v[96:97]
	global_store_dword v[58:59], v62, off
